# P10 FFN-down tile order: 4 row-blocks x 8 col-blocks per XCD per round so each ACT row block streams from HBM once (was twice)
# baseline (speedup 1.0000x reference)
.LBB0_1551:
	v_ashrrev_i32_e32 v1, 31, v216
	v_lshrrev_b32_e32 v1, 26, v1
	v_add_u32_e32 v1, v216, v1
	v_ashrrev_i32_e32 v8, 6, v1
	v_bfe_i32 v1, v216, 27, 1
	v_lshlrev_b32_e32 v0, 4, v216
	v_lshrrev_b32_e32 v1, 22, v1
	v_add_u32_e32 v1, v0, v1
	v_and_b32_e32 v1, 0xfffffc00, v1
	v_sub_u32_e32 v1, v0, v1
	v_lshrrev_b32_e32 v2, 4, v1
	v_bitop3_b32 v1, v2, v1, 32 bitop3:0x6c
	v_ashrrev_i32_e32 v3, 31, v1
	v_lshrrev_b32_e32 v3, 26, v3
	v_lshlrev_b32_e32 v2, 3, v8
	v_add_u32_e32 v3, v1, v3
	v_and_b32_e32 v2, -16, v2
	v_ashrrev_i32_e32 v9, 6, v3
	v_and_b32_e32 v3, 0xc0, v3
	v_readlane_b32 s6, v254, 14
	v_add_u32_e32 v2, v9, v2
	v_lshlrev_b32_e32 v4, 5, v8
	v_sub_u32_e32 v1, v1, v3
	v_mov_b32_e32 v3, 1
	v_readlane_b32 s7, v254, 15
	s_add_u32 s3, s6, 0x6400000
	v_and_b32_e32 v10, 32, v4
	v_ashrrev_i16_sdwa v1, v3, sext(v1) dst_sel:DWORD dst_unused:UNUSED_PAD src0_sel:DWORD src1_sel:BYTE_0
	v_lshlrev_b32_e32 v4, 1, v2
	v_lshrrev_b32_e32 v5, 2, v2
	v_and_b32_e32 v6, 3, v9
	s_mov_b32 s9, 0x7fffe0
	s_addc_u32 s19, s7, 0
	v_bfe_i32 v11, v1, 0, 16
	v_and_b32_e32 v4, 24, v4
	v_and_b32_e32 v5, 4, v5
	v_and_or_b32 v6, v2, s9, v6
	s_movk_i32 s7, 0x1600
	v_add_u32_e32 v1, v10, v11
	v_or3_b32 v4, v6, v5, v4
	v_mul_lo_u32 v2, v2, s7
	v_add_lshl_u32 v130, v1, v2, 1
	v_mul_u32_u24_e32 v2, 0x1600, v4
	v_add_u32_e32 v0, 0x2000, v0
	v_add_lshl_u32 v132, v2, v1, 1
	v_ashrrev_i32_e32 v1, 31, v0
	v_lshrrev_b32_e32 v1, 22, v1
	s_add_i32 s8, s8, s10
	v_add_u32_e32 v1, v0, v1
	s_ashr_i32 s10, s8, 31
	v_ashrrev_i32_e32 v12, 10, v1
	s_lshr_b32 s10, s10, 26
	v_mul_i32_i24_e32 v1, 0x400, v12
	s_add_i32 s10, s8, s10
	v_sub_u32_e32 v0, v0, v1
	s_ashr_i32 s11, s10, 6
	s_and_b32 s10, s10, 0xffc0
	v_lshrrev_b32_e32 v1, 4, v0
	s_sub_i32 s10, s8, s10
	v_bitop3_b32 v0, v1, v0, 32 bitop3:0x6c
	s_bfe_i32 s8, s10, 0x80000
	v_ashrrev_i32_e32 v2, 31, v0
	s_bfe_u32 s8, s8, 0x3000c
	v_lshrrev_b32_e32 v2, 26, v2
	s_add_i32 s12, s10, s8
	v_lshlrev_b32_e32 v1, 3, v12
	v_add_u32_e32 v2, v0, v2
	s_bfe_i32 s8, s12, 0x80000
	s_and_b32 s12, s12, 0xf8
	v_and_b32_e32 v1, -16, v1
	v_ashrrev_i32_e32 v13, 6, v2
	v_lshlrev_b32_e32 v4, 5, v12
	s_sub_i32 s10, s10, s12
	v_add_u32_e32 v1, v13, v1
	v_and_b32_e32 v14, 32, v4
	v_and_b32_e32 v4, 3, v13
	s_lshl_b32 s11, s11, 3
	s_sext_i32_i16 s13, s8
	s_sext_i32_i8 s10, s10
	v_and_b32_e32 v2, 0xc0, v2
	v_and_or_b32 v4, v1, s9, v4
	s_ashr_i32 s9, s0, 6
	s_add_i32 s14, s11, s10
	s_and_b32 s12, s10, 3
	s_lshr_b32 s15, s10, 2
	s_lshr_b32 s11, s13, 3
	s_andn2_b32 s14, s14, 7
	s_add_i32 s14, s14, s12
	s_lshr_b32 s12, s11, 2
	s_lshl_b32 s12, s12, 2
	s_add_i32 s14, s14, s12
	s_and_b32 s11, s11, 3
	s_lshl_b32 s11, s11, 1
	s_add_i32 s11, s11, s15
	s_lshl_b32 s13, s11, 3
	s_ashr_i32 s10, s13, 3
	s_ashr_i32 s6, s0, 8
	v_sub_u32_e32 v0, v0, v2
	s_lshl_b32 s30, s9, 10
	s_lshr_b32 s8, s13, 3
	s_mul_hi_i32 s11, s10, 0x2c0000
	s_mul_i32 s10, s10, 0x2c0000
	v_ashrrev_i16_sdwa v0, v3, sext(v0) dst_sel:DWORD dst_unused:UNUSED_PAD src0_sel:DWORD src1_sel:BYTE_0
	v_lshlrev_b32_e32 v2, 1, v1
	v_lshrrev_b32_e32 v3, 2, v1
	s_add_u32 s22, s3, s10
	v_bfe_i32 v15, v0, 0, 16
	v_and_b32_e32 v2, 24, v2
	v_and_b32_e32 v3, 4, v3
	s_addc_u32 s23, s19, s11
	s_add_i32 s31, s30, 0
	v_add_u32_e32 v0, v14, v15
	v_or3_b32 v2, v4, v3, v2
	v_mul_lo_u32 v1, v1, s7
	s_add_i32 m0, s31, 0x10000
	v_add_lshl_u32 v134, v0, v1, 1
	v_mul_u32_u24_e32 v1, 0x1600, v2
	global_load_lds_dwordx4 v132, s[22:23]
	s_add_i32 m0, s31, 0x12000
	v_add_lshl_u32 v136, v1, v0, 1
	s_add_u32 s10, s22, 0x160000
	global_load_lds_dwordx4 v136, s[22:23]
	s_addc_u32 s11, s23, 0
	s_add_i32 m0, s31, 0x14000
	s_mul_i32 s15, s14, 0x2c0000
	global_load_lds_dwordx4 v132, s[10:11]
	s_add_i32 m0, s31, 0x16000
	s_mul_hi_i32 s12, s14, 0x2c0000
	s_add_u32 s20, s26, s15
	s_addc_u32 s21, s27, s12
	s_add_i32 s36, s31, 0x2000
	global_load_lds_dwordx4 v136, s[10:11]
	s_mov_b32 m0, s31
	s_add_u32 s10, s20, 0x160000
	global_load_lds_dwordx4 v130, s[20:21]
	s_mov_b32 m0, s36
	s_addc_u32 s11, s21, 0
	s_add_i32 s37, s31, 0x4000
	global_load_lds_dwordx4 v134, s[20:21]
	s_mov_b32 m0, s37
	s_add_i32 s38, s31, 0x6000
	global_load_lds_dwordx4 v130, s[10:11]
	s_mov_b32 m0, s38
	v_mov_b32_e32 v133, 0
	global_load_lds_dwordx4 v134, s[10:11]
	v_readlane_b32 s10, v254, 3
	v_readlane_b32 s11, v254, 4
	s_load_dwordx2 s[12:13], s[10:11], 0xc0
	v_mov_b32_e32 v137, v133
	v_mov_b32_e32 v131, v133
	v_mov_b32_e32 v135, v133
	s_mov_b32 s39, 0
	v_lshl_add_u64 v[6:7], s[22:23], 0, v[132:133]
	v_lshl_add_u64 v[4:5], s[22:23], 0, v[136:137]
	s_mov_b32 s10, 0x16000
	v_lshl_add_u64 v[2:3], s[20:21], 0, v[130:131]
	s_cmp_lg_u32 s6, 1
	v_lshl_add_u64 v[0:1], s[20:21], 0, v[134:135]
	s_cbranch_scc1 .LBB0_1553
	s_barrier

.LBB0_1559:
	s_ashr_i32 s10, s24, 3
	s_add_i32 s10, s28, s10
	s_ashr_i32 s11, s10, 31
	s_lshr_b32 s11, s11, 26
	s_add_i32 s11, s10, s11
	s_ashr_i32 s24, s11, 6
	s_lshl_b32 s24, s24, 3
	s_sub_i32 s25, 64, s24
	s_min_i32 s25, s25, 8
	s_abs_i32 s28, s25
	v_cvt_f32_u32_e32 v0, s28
	s_sub_i32 s33, 0, s28
	s_andn2_b32 s11, s11, 63
	s_sub_i32 s10, s10, s11
	v_rcp_iflag_f32_e32 v0, v0
	s_abs_i32 s11, s10
	s_xor_b32 s29, s10, s25
	s_ashr_i32 s29, s29, 31
	v_mul_f32_e32 v0, 0x4f7ffffe, v0
	v_cvt_u32_f32_e32 v0, v0
	s_nop 0
	v_readfirstlane_b32 s34, v0
	s_mul_i32 s33, s33, s34
	s_mul_hi_u32 s33, s34, s33
	s_add_i32 s34, s34, s33
	s_mul_hi_u32 s33, s11, s34
	s_mul_i32 s34, s33, s28
	s_sub_i32 s11, s11, s34
	s_add_i32 s35, s33, 1
	s_sub_i32 s34, s11, s28
	s_cmp_ge_u32 s11, s28
	s_cselect_b32 s33, s35, s33
	s_cselect_b32 s11, s34, s11
	s_add_i32 s34, s33, 1
	s_cmp_ge_u32 s11, s28
	s_cselect_b32 s11, s34, s33
	s_xor_b32 s11, s11, s29
	s_sub_i32 s48, s11, s29
	s_mul_i32 s11, s48, s25
	s_sub_i32 s10, s10, s11
	s_add_i32 s49, s24, s10
	s_and_b32 s10, s49, 7
	s_lshr_b32 s11, s48, 2
	s_and_b32 s33, s48, 3
	s_andn2_b32 s49, s49, 7
	s_lshl_b32 s34, s11, 2
	s_add_i32 s49, s49, s34
	s_and_b32 s34, s10, 3
	s_add_i32 s49, s49, s34
	s_lshr_b32 s10, s10, 2
	s_lshl_b32 s33, s33, 1
	s_add_i32 s48, s33, s10
